# transpose vmcnt fix plus attention K/V tile L2 prefetch two tiles ahead
# baseline (speedup 1.0000x reference)
; __device__ __forceinline__ unsigned cvt_pk_bf16(float lo, float hi) { f32x2_t f = {lo, hi}; bf16x2_t r = __builtin_convertvector(f, bf16x2_t); return __builtin_bit_cast(unsigned, r); }
; #define LAS __attribute__((address_space(3)))
; #define MFMA32(a, b, c) __builtin_amdgcn_mfma_f32_32x32x16_bf16((a), (b), (c), 0, 0, 0)
; template <bool DIFF> ...
;     ...
;     auto store_tile = [&](int buf) {
;         LAS unsigned char* kb_ = lds + buf * BUF; LAS unsigned char* vb_ = kb_ + K_BYTES;
; #pragma unroll
;         for (int i = 0; i < NKC; ++i) { const int c = tid + i * NTHREADS, row = c / CPR, cc = c % CPR; *(LAS u32x4*)(kb_ + (row * KSTR + cc * 8) * 2) = kreg[i]; }
; #pragma unroll
;         for (int i = 0; i < 2; ++i) { const int c = tid + i * NTHREADS, dv = c >> 3, cc = c & 7; *(LAS u32x4*)(vb_ + (dv * VSTR + cc * 8) * 2) = vreg[i]; }
;     };
;     ...
; #pragma unroll
;             for (int kb = 0; kb < 2; ++kb)
; #pragma unroll
;                 for (int i = 0; i < 16; ++i) { const float p = __builtin_amdgcn_exp2f(s[kb][i] - m_used); s[kb][i] = p; lsum += p; }
;         }
; #pragma unroll
;         for (int kb = 0; kb < 2; ++kb)
; #pragma unroll
;             for (int st = 0; st < 2; ++st) {
;                 u32x4 pw;
; #pragma unroll
;                 for (int q = 0; q < 4; ++q) pw[q] = cvt_pk_bf16(s[kb][8 * st + 2 * q], s[kb][8 * st + 2 * q + 1]);
;                 const bf16x8 pf = __builtin_bit_cast(bf16x8, pw);
;                 const LAS unsigned char* vp = vbuf + (r * VSTR + (2 * kb + st) * 16 + 8 * hh) * 2;
; #pragma unroll
;                 for (int d = 0; d < 4; ++d) { const bf16x8 vf = *(const LAS bf16x8*)(vp + d * 32 * VSTR * 2); O[d] = MFMA32(vf, pf, O[d]); }
;             }
;         if (more) store_tile((kt + 1) & 1);
;         __syncthreads();
.LBB0_568:
	v_sub_f32_e32 v0, v96, v190
	v_sub_f32_e32 v96, v99, v190
	v_exp_f32_e32 v212, v96
	v_sub_f32_e32 v96, v100, v190
	v_exp_f32_e32 v213, v96
	v_sub_f32_e32 v96, v101, v190
	v_add_u32_e32 v215, s26, v189
	v_sub_f32_e32 v14, v97, v190
	v_sub_f32_e32 v15, v98, v190
	v_exp_f32_e32 v214, v96
	ds_read_b128 v[96:99], v215 offset:25600
	ds_read_b128 v[200:203], v215 offset:25632
	v_sub_f32_e32 v100, v102, v190
	v_exp_f32_e32 v216, v100
	v_sub_f32_e32 v100, v103, v190
	v_exp_f32_e32 v0, v0
	v_exp_f32_e32 v14, v14
	v_exp_f32_e32 v15, v15
	v_exp_f32_e32 v217, v100
	v_cvt_pk_bf16_f32 v102, v213, v214
	v_cvt_pk_bf16_f32 v100, v0, v14
	v_cvt_pk_bf16_f32 v101, v15, v212
	v_cvt_pk_bf16_f32 v103, v216, v217
	v_sub_f32_e32 v104, v104, v190
	v_exp_f32_e32 v218, v104
	s_waitcnt lgkmcnt(1)
	v_mfma_f32_32x32x16_bf16 v[64:79], v[96:99], v[100:103], v[64:79]
	ds_read_b128 v[96:99], v215 offset:30208
	ds_read_b128 v[204:207], v215 offset:34816
	ds_read_b128 v[208:211], v215 offset:30240
	v_sub_f32_e32 v222, v107, v190
	v_sub_f32_e32 v108, v108, v190
	v_sub_f32_e32 v109, v109, v190
	v_sub_f32_e32 v110, v110, v190
	v_exp_f32_e32 v222, v222
	s_waitcnt lgkmcnt(2)
	v_mfma_f32_32x32x16_bf16 v[48:63], v[96:99], v[100:103], v[48:63]
	v_sub_f32_e32 v96, v105, v190
	v_exp_f32_e32 v219, v96
	v_sub_f32_e32 v96, v106, v190
	v_exp_f32_e32 v221, v96
	ds_read_b128 v[96:99], v215 offset:39424
	ds_read_b128 v[104:107], v215 offset:34848
	v_exp_f32_e32 v108, v108
	v_exp_f32_e32 v109, v109
	s_waitcnt lgkmcnt(1)
	v_mfma_f32_32x32x16_bf16 v[16:31], v[96:99], v[100:103], v[16:31]
	v_sub_f32_e32 v96, v111, v190
	v_exp_f32_e32 v110, v110
	v_exp_f32_e32 v111, v96
	v_cvt_pk_bf16_f32 v96, v218, v219
	v_cvt_pk_bf16_f32 v97, v221, v222
	v_cvt_pk_bf16_f32 v98, v108, v109
	v_cvt_pk_bf16_f32 v99, v110, v111
	v_sub_f32_e32 v80, v80, v190
	v_mfma_f32_32x32x16_bf16 v[32:47], v[204:207], v[100:103], v[32:47]
	ds_read_b128 v[204:207], v215 offset:39456
	v_add_f32_e32 v0, v188, v0
	v_add_f32_e32 v0, v14, v0
	v_add_f32_e32 v0, v15, v0
	v_add_f32_e32 v0, v212, v0
	v_add_f32_e32 v0, v213, v0
	v_add_f32_e32 v0, v214, v0
	v_mfma_f32_32x32x16_bf16 v[64:79], v[200:203], v[96:99], v[64:79]
	v_exp_f32_e32 v200, v80
	v_sub_f32_e32 v80, v81, v190
	v_exp_f32_e32 v201, v80
	v_sub_f32_e32 v80, v82, v190
	v_exp_f32_e32 v202, v80
	v_sub_f32_e32 v80, v83, v190
	v_exp_f32_e32 v203, v80
	v_sub_f32_e32 v80, v84, v190
	v_mfma_f32_32x32x16_bf16 v[48:63], v[208:211], v[96:99], v[48:63]
	v_exp_f32_e32 v208, v80
	v_sub_f32_e32 v80, v85, v190
	v_exp_f32_e32 v209, v80
	v_sub_f32_e32 v80, v86, v190
	v_exp_f32_e32 v210, v80
	ds_read_b128 v[80:83], v215 offset:25664
	v_sub_f32_e32 v84, v87, v190
	s_waitcnt lgkmcnt(1)
	v_mfma_f32_32x32x16_bf16 v[16:31], v[204:207], v[96:99], v[16:31]
	v_exp_f32_e32 v204, v84
	v_cvt_pk_bf16_f32 v84, v200, v201
	v_cvt_pk_bf16_f32 v85, v202, v203
	v_cvt_pk_bf16_f32 v86, v208, v209
	v_cvt_pk_bf16_f32 v87, v210, v204
	v_add_f32_e32 v0, v216, v0
	v_add_f32_e32 v0, v217, v0
	v_mfma_f32_32x32x16_bf16 v[32:47], v[104:107], v[96:99], v[32:47]
	ds_read_b128 v[96:99], v215 offset:25696
	v_add_f32_e32 v0, v218, v0
	v_add_f32_e32 v0, v219, v0
	v_add_f32_e32 v0, v221, v0
	v_add_f32_e32 v0, v222, v0
	v_add_f32_e32 v0, v108, v0
	v_add_f32_e32 v0, v109, v0
	s_waitcnt lgkmcnt(1)
	v_mfma_f32_32x32x16_bf16 v[64:79], v[80:83], v[84:87], v[64:79]
	ds_read_b128 v[80:83], v215 offset:30272
	v_add_f32_e32 v0, v110, v0
	v_sub_f32_e32 v88, v88, v190
	ds_read_b128 v[100:103], v215 offset:34880
	ds_read_b128 v[104:107], v215 offset:30304
	v_add_f32_e32 v0, v111, v0
	v_exp_f32_e32 v205, v88
	v_sub_f32_e32 v211, v91, v190
	s_waitcnt lgkmcnt(2)
	v_mfma_f32_32x32x16_bf16 v[48:63], v[80:83], v[84:87], v[48:63]
	v_sub_f32_e32 v80, v89, v190
	v_exp_f32_e32 v206, v80
	v_sub_f32_e32 v80, v90, v190
	v_exp_f32_e32 v207, v80
	ds_read_b128 v[80:83], v215 offset:39488
	ds_read_b128 v[88:91], v215 offset:34912
	v_add_f32_e32 v0, v200, v0
	v_add_f32_e32 v0, v201, v0
	v_add_f32_e32 v0, v202, v0
	s_waitcnt lgkmcnt(3)
	v_mfma_f32_32x32x16_bf16 v[32:47], v[100:103], v[84:87], v[32:47]
	ds_read_b128 v[100:103], v215 offset:39520
	v_add_f32_e32 v0, v203, v0
	v_add_f32_e32 v0, v208, v0
	v_add_f32_e32 v0, v209, v0
	v_sub_f32_e32 v92, v92, v190
	v_sub_f32_e32 v93, v93, v190
	v_sub_f32_e32 v94, v94, v190
	s_waitcnt lgkmcnt(2)
	v_mfma_f32_32x32x16_bf16 v[16:31], v[80:83], v[84:87], v[16:31]
	v_sub_f32_e32 v80, v95, v190
	v_add_f32_e32 v0, v210, v0
	v_exp_f32_e32 v211, v211
	v_exp_f32_e32 v92, v92
	v_exp_f32_e32 v93, v93
	v_exp_f32_e32 v84, v94
	v_exp_f32_e32 v85, v80
	v_add_f32_e32 v0, v204, v0
	v_add_f32_e32 v0, v205, v0
	v_add_f32_e32 v0, v206, v0
	v_add_f32_e32 v0, v207, v0
	v_cvt_pk_bf16_f32 v80, v205, v206
	v_cvt_pk_bf16_f32 v81, v207, v211
	v_cvt_pk_bf16_f32 v82, v92, v93
	v_cvt_pk_bf16_f32 v83, v84, v85
	s_add_i32 s12, s12, 1
	v_add_f32_e32 v0, v211, v0
	v_mfma_f32_32x32x16_bf16 v[64:79], v[96:99], v[80:83], v[64:79]
	v_add_f32_e32 v0, v92, v0
	s_bitcmp1_b32 s12, 0
	v_add_f32_e32 v0, v93, v0
	s_cselect_b32 s26, 0xac00, 0
	v_add_f32_e32 v0, v84, v0
	s_add_i32 s26, s26, 0
	v_add_f32_e32 v188, v85, v0
	v_mfma_f32_32x32x16_bf16 v[48:63], v[104:107], v[80:83], v[48:63]
	v_add3_u32 v0, s26, v191, v192
	s_waitcnt vmcnt(9)
	ds_write_b128 v0, v[10:13]
	v_add3_u32 v0, s26, v193, v194
	s_waitcnt vmcnt(8)
	ds_write_b128 v0, v[2:5]
	v_add3_u32 v0, s26, v195, v196
	s_waitcnt vmcnt(7)
	ds_write_b128 v0, v[160:163]
	v_add_u32_e32 v0, s26, v197
	s_waitcnt lgkmcnt(4)
	v_mfma_f32_32x32x16_bf16 v[32:47], v[88:91], v[80:83], v[32:47]
	s_waitcnt vmcnt(6)
	ds_write_b128 v0, v[6:9] offset:25600
	v_add_u32_e32 v0, s26, v198
	v_lshl_add_u64 v[170:171], v[170:171], 0, s[20:21]
	v_lshl_add_u64 v[172:173], v[172:173], 0, s[20:21]
	v_lshl_add_u64 v[174:175], v[174:175], 0, s[22:23]
	v_lshl_add_u64 v[176:177], v[176:177], 0, s[22:23]
	s_cmp_eq_u32 s12, 31
	s_waitcnt lgkmcnt(4)
	v_mfma_f32_32x32x16_bf16 v[16:31], v[100:103], v[80:83], v[16:31]
	v_lshl_add_u64 v[178:179], v[178:179], 0, s[22:23]
	s_waitcnt vmcnt(5)
	ds_write_b128 v0, v[164:167] offset:25600
	s_waitcnt lgkmcnt(0)
	s_barrier
	s_cbranch_scc1 .LBB0_571
; #define LAS __attribute__((address_space(3)))
; template <bool DIFF> ...
;     ...
;     auto load_tile = [&](int kt) {
; #pragma unroll
;         for (int i = 0; i < NKC; ++i) { const int c = tid + i * NTHREADS, row = c / CPR, cc = c % CPR; kreg[i] = *(const u32x4*)(Kb + (size_t)(kt * 64 + row) * KLD + cc * 8); }
; #pragma unroll
;         for (int i = 0; i < 2; ++i) { const int c = tid + i * NTHREADS, dv = c >> 3, cc = c & 7; vreg[i] = *(const u32x4*)(Vb + (size_t)dv * SEQ + kt * 64 + cc * 8); }
;     };
;     ...
;     for (int kt = 0; kt < SEQ / 64; ++kt) {
;         const bool more = kt + 1 < SEQ / 64;
;         if (more) load_tile(kt + 1);
;         LAS unsigned char* kbuf = lds + (kt & 1) * BUF; LAS unsigned char* vbuf = kbuf + K_BYTES;
;         f32x16 s[2];
;         if (DIFF) {
;             const int tmn = ((const LAS int*)(lds + TMM_OFF))[2 * kt], tmx = ((const LAS int*)(lds + TMM_OFF))[2 * kt + 1];
;             const bool far_hi = __builtin_amdgcn_readfirstlane(tmn - qmax4) >= 512, far_lo = __builtin_amdgcn_readfirstlane(tmx - qmin4) <= -512;
;             if (far_hi || far_lo) {
;                 const float cb = (far_hi ? bias_hi : bias_lo) + nm;
; #pragma unroll
;                 for (int kb = 0; kb < 2; ++kb)
; #pragma unroll
;                     for (int i = 0; i < 16; ++i) s[kb][i] = cb;
;             } else {
; #pragma unroll
;                 for (int kb = 0; kb < 2; ++kb) {
;                     const LAS int* P4 = (const LAS int*)(lds + POS_OFF) + kt * 64 + 32 * kb + 4 * hh;
; #pragma unroll
;                     for (int g = 0; g < 4; ++g) { const i32x4 pk = *(const LAS i32x4*)(P4 + 8 * g);
; #pragma unroll
;                         for (int j = 0; j < 4; ++j) { int d = pk[j] - pq4; d = d < -512 ? -512 : (d > 512 ? 512 : d); s[kb][4 * g + j] = *(const LAS float*)(lds + LUT_OFF + 512 + d) + nm; } }
;                 }
;             }
;         } else {
; #pragma unroll
;             for (int kb = 0; kb < 2; ++kb)
; #pragma unroll
;                 for (int i = 0; i < 16; ++i) s[kb][i] = 0.f;
;         }
;         {
;             const LAS unsigned char* kp0 = kbuf + (r * KSTR + hf * 64 + 8 * hh) * 2; const LAS unsigned char* kp1 = kp0 + 32 * KSTR * 2;
; #pragma unroll
;             for (int ks = 0; ks < NKS; ++ks) { const bf16x8 kf0 = *(const LAS bf16x8*)(kp0 + 32 * ks), kf1 = *(const LAS bf16x8*)(kp1 + 32 * ks);
.LBB0_569:
	s_bitcmp1_b32 s12, 0
	s_cselect_b32 s26, 0xac00, 0
	s_add_i32 s26, s26, 0
	v_add_u32_e32 v0, s26, v199
	ds_read_b128 v[2:5], v0
	ds_read_b128 v[6:9], v0 offset:32
	v_lshl_add_u64 v[14:15], s[8:9], 0, v[172:173]
	s_waitcnt lgkmcnt(1)
	v_mfma_f32_32x32x16_bf16 v[96:111], v[2:5], v[156:159], 0
	ds_read_b128 v[2:5], v0 offset:12800
	ds_read_b128 v[10:13], v0 offset:12832
	s_waitcnt lgkmcnt(1)
	v_mfma_f32_32x32x16_bf16 v[80:95], v[2:5], v[156:159], 0
	v_mfma_f32_32x32x16_bf16 v[96:111], v[6:9], v[152:155], v[96:111]
	ds_read_b128 v[2:5], v0 offset:64
	ds_read_b128 v[6:9], v0 offset:96
	s_waitcnt lgkmcnt(2)
	v_mfma_f32_32x32x16_bf16 v[80:95], v[10:13], v[152:155], v[80:95]
	s_waitcnt lgkmcnt(1)
	v_mfma_f32_32x32x16_bf16 v[96:111], v[2:5], v[148:151], v[96:111]
	ds_read_b128 v[2:5], v0 offset:12864
	ds_read_b128 v[10:13], v0 offset:12896
	s_waitcnt lgkmcnt(1)
	v_mfma_f32_32x32x16_bf16 v[80:95], v[2:5], v[148:151], v[80:95]
	v_mfma_f32_32x32x16_bf16 v[96:111], v[6:9], v[144:147], v[96:111]
	ds_read_b128 v[2:5], v0 offset:128
	ds_read_b128 v[6:9], v0 offset:160
	s_waitcnt lgkmcnt(2)
	v_mfma_f32_32x32x16_bf16 v[80:95], v[10:13], v[144:147], v[80:95]
	s_waitcnt lgkmcnt(1)
	v_mfma_f32_32x32x16_bf16 v[96:111], v[2:5], v[140:143], v[96:111]
	ds_read_b128 v[2:5], v0 offset:12928
	ds_read_b128 v[10:13], v0 offset:12960
	s_waitcnt lgkmcnt(1)
	v_mfma_f32_32x32x16_bf16 v[80:95], v[2:5], v[140:143], v[80:95]
	v_mfma_f32_32x32x16_bf16 v[96:111], v[6:9], v[136:139], v[96:111]
	ds_read_b128 v[2:5], v0 offset:192
	ds_read_b128 v[6:9], v0 offset:224
	s_waitcnt lgkmcnt(2)
	v_mfma_f32_32x32x16_bf16 v[80:95], v[10:13], v[136:139], v[80:95]
	s_waitcnt lgkmcnt(1)
	v_mfma_f32_32x32x16_bf16 v[96:111], v[2:5], v[132:135], v[96:111]
	ds_read_b128 v[2:5], v0 offset:12992
	ds_read_b128 v[10:13], v0 offset:13024
	s_waitcnt lgkmcnt(1)
	v_mfma_f32_32x32x16_bf16 v[80:95], v[2:5], v[132:135], v[80:95]
	v_mfma_f32_32x32x16_bf16 v[96:111], v[6:9], v[128:131], v[96:111]
	ds_read_b128 v[2:5], v0 offset:256
	ds_read_b128 v[6:9], v0 offset:288
	s_waitcnt lgkmcnt(2)
	v_mfma_f32_32x32x16_bf16 v[80:95], v[10:13], v[128:131], v[80:95]
	s_waitcnt lgkmcnt(1)
	v_mfma_f32_32x32x16_bf16 v[96:111], v[2:5], v[124:127], v[96:111]
	ds_read_b128 v[2:5], v0 offset:13056
	ds_read_b128 v[10:13], v0 offset:13088
	ds_read_b128 v[164:167], v0 offset:320
	s_waitcnt lgkmcnt(2)
	v_mfma_f32_32x32x16_bf16 v[80:95], v[2:5], v[124:127], v[80:95]
	v_lshl_add_u64 v[2:3], s[8:9], 0, v[178:179]
	v_lshl_add_u64 v[4:5], s[8:9], 0, v[176:177]
	v_mfma_f32_32x32x16_bf16 v[96:111], v[6:9], v[120:123], v[96:111]
	v_lshl_add_u64 v[6:7], s[8:9], 0, v[174:175]
	v_lshl_add_u64 v[8:9], s[8:9], 0, v[170:171]
	s_waitcnt lgkmcnt(1)
	v_mfma_f32_32x32x16_bf16 v[80:95], v[10:13], v[120:123], v[80:95]
	global_load_dwordx4 v[10:13], v[2:3], off
	s_nop 0
	global_load_dwordx4 v[2:5], v[4:5], off
	s_nop 0
	global_load_dwordx4 v[160:163], v[6:7], off
	s_nop 0
	global_load_dwordx4 v[6:9], v[8:9], off
	ds_read_b128 v[200:203], v0 offset:352
	s_waitcnt lgkmcnt(1)
	v_mfma_f32_32x32x16_bf16 v[96:111], v[164:167], v[116:119], v[96:111]
	global_load_dwordx4 v[164:167], v[14:15], off
	s_cmp_lt_u32 s12, 30
	s_cselect_b32 s98, 0x30000, 0
	s_cselect_b32 s100, 0x80, 0
	s_add_u32 s98, s98, s8
	s_addc_u32 s99, s9, 0
	s_add_u32 s100, s100, s8
	s_addc_u32 s101, s9, 0
	v_lshl_add_u64 v[224:225], s[98:99], 0, v[178:179]
	global_load_dword v223, v[224:225], off
	v_lshl_add_u64 v[224:225], s[98:99], 0, v[176:177]
	global_load_dword v223, v[224:225], off
	v_lshl_add_u64 v[224:225], s[98:99], 0, v[174:175]
	global_load_dword v223, v[224:225], off
	v_lshl_add_u64 v[224:225], s[100:101], 0, v[170:171]
	global_load_dword v223, v[224:225], off
	v_lshl_add_u64 v[224:225], s[100:101], 0, v[172:173]
	global_load_dword v223, v[224:225], off
	s_waitcnt lgkmcnt(0)
	v_mfma_f32_32x32x16_bf16 v[96:111], v[200:203], v[112:115], v[96:111]
	ds_read_b128 v[200:203], v0 offset:13120
	ds_read_b128 v[204:207], v0 offset:13152
	s_waitcnt lgkmcnt(1)
	v_mfma_f32_32x32x16_bf16 v[80:95], v[200:203], v[116:119], v[80:95]
	s_nop 7
	v_max_f32_e32 v0, v97, v97
	v_max_f32_e32 v14, v96, v96
	v_max_f32_e32 v0, v14, v0
	v_max3_f32 v0, v0, v98, v99
	v_max3_f32 v0, v0, v100, v101
	v_max3_f32 v0, v0, v102, v103
	v_max3_f32 v0, v0, v104, v105
	s_waitcnt lgkmcnt(0)
	v_mfma_f32_32x32x16_bf16 v[80:95], v[204:207], v[112:115], v[80:95]
	v_max3_f32 v0, v0, v106, v107
	v_max3_f32 v0, v0, v108, v109
	v_max3_f32 v0, v0, v110, v111
	s_nop 8
	v_max3_f32 v0, v0, v80, v81
	v_max3_f32 v0, v0, v82, v83
	v_max3_f32 v0, v0, v84, v85
	v_max3_f32 v0, v0, v86, v87
	v_max3_f32 v0, v0, v88, v89
	v_max3_f32 v0, v0, v90, v91
	v_max3_f32 v0, v0, v92, v93
	v_max3_f32 v0, v0, v94, v95
	ds_bpermute_b32 v14, v187, v0
	s_waitcnt lgkmcnt(0)
	v_max_f32_e32 v14, v14, v14
	v_max_f32_e32 v0, v0, v14
	v_add_f32_e32 v14, 0x41000000, v190
	v_cmp_gt_f32_e32 vcc, v0, v14
	s_cbranch_vccz .LBB0_568
	s_nop 0
	v_cndmask_b32_e32 v14, v190, v0, vcc
	v_sub_f32_e32 v0, v190, v14
	v_exp_f32_e32 v0, v0
	v_mov_b32_e32 v190, v14
	v_pk_mul_f32 v[78:79], v[78:79], v[0:1] op_sel_hi:[1,0]
	v_pk_mul_f32 v[76:77], v[76:77], v[0:1] op_sel_hi:[1,0]
	v_pk_mul_f32 v[74:75], v[74:75], v[0:1] op_sel_hi:[1,0]
	v_pk_mul_f32 v[72:73], v[72:73], v[0:1] op_sel_hi:[1,0]
	v_pk_mul_f32 v[70:71], v[70:71], v[0:1] op_sel_hi:[1,0]
	v_pk_mul_f32 v[68:69], v[68:69], v[0:1] op_sel_hi:[1,0]
	v_pk_mul_f32 v[66:67], v[66:67], v[0:1] op_sel_hi:[1,0]
	v_pk_mul_f32 v[64:65], v[64:65], v[0:1] op_sel_hi:[1,0]
	v_pk_mul_f32 v[62:63], v[62:63], v[0:1] op_sel_hi:[1,0]
	v_pk_mul_f32 v[60:61], v[60:61], v[0:1] op_sel_hi:[1,0]
	v_pk_mul_f32 v[58:59], v[58:59], v[0:1] op_sel_hi:[1,0]
	v_pk_mul_f32 v[56:57], v[56:57], v[0:1] op_sel_hi:[1,0]
	v_pk_mul_f32 v[54:55], v[54:55], v[0:1] op_sel_hi:[1,0]
	v_pk_mul_f32 v[52:53], v[52:53], v[0:1] op_sel_hi:[1,0]
	v_pk_mul_f32 v[50:51], v[50:51], v[0:1] op_sel_hi:[1,0]
	v_pk_mul_f32 v[48:49], v[48:49], v[0:1] op_sel_hi:[1,0]
	v_pk_mul_f32 v[46:47], v[46:47], v[0:1] op_sel_hi:[1,0]
	v_pk_mul_f32 v[44:45], v[44:45], v[0:1] op_sel_hi:[1,0]
	v_pk_mul_f32 v[42:43], v[42:43], v[0:1] op_sel_hi:[1,0]
	v_pk_mul_f32 v[40:41], v[40:41], v[0:1] op_sel_hi:[1,0]
	v_pk_mul_f32 v[38:39], v[38:39], v[0:1] op_sel_hi:[1,0]
	v_pk_mul_f32 v[36:37], v[36:37], v[0:1] op_sel_hi:[1,0]
	v_pk_mul_f32 v[34:35], v[34:35], v[0:1] op_sel_hi:[1,0]
	v_pk_mul_f32 v[32:33], v[32:33], v[0:1] op_sel_hi:[1,0]
	v_pk_mul_f32 v[30:31], v[30:31], v[0:1] op_sel_hi:[1,0]
	v_pk_mul_f32 v[28:29], v[28:29], v[0:1] op_sel_hi:[1,0]
	v_pk_mul_f32 v[26:27], v[26:27], v[0:1] op_sel_hi:[1,0]
	v_pk_mul_f32 v[24:25], v[24:25], v[0:1] op_sel_hi:[1,0]
	v_pk_mul_f32 v[22:23], v[22:23], v[0:1] op_sel_hi:[1,0]
	v_pk_mul_f32 v[20:21], v[20:21], v[0:1] op_sel_hi:[1,0]
	v_pk_mul_f32 v[18:19], v[18:19], v[0:1] op_sel_hi:[1,0]
	v_pk_mul_f32 v[16:17], v[16:17], v[0:1] op_sel_hi:[1,0]
	v_mul_f32_e32 v188, v188, v0
	s_branch .LBB0_568

; __device__ __forceinline__ unsigned cvt_pk_bf16(float lo, float hi) { f32x2_t f = {lo, hi}; bf16x2_t r = __builtin_convertvector(f, bf16x2_t); return __builtin_bit_cast(unsigned, r); }
; #define LAS __attribute__((address_space(3)))
; template <bool DIFF> ...
;     ...
;     auto store_tile = [&](int buf) {
;         LAS unsigned char* kb_ = lds + buf * BUF; LAS unsigned char* vb_ = kb_ + K_BYTES;
; #pragma unroll
;         for (int i = 0; i < NKC; ++i) { const int c = tid + i * NTHREADS, row = c / CPR, cc = c % CPR; *(LAS u32x4*)(kb_ + (row * KSTR + cc * 8) * 2) = kreg[i]; }
; #pragma unroll
;         for (int i = 0; i < 2; ++i) { const int c = tid + i * NTHREADS, dv = c >> 3, cc = c & 7; *(LAS u32x4*)(vb_ + (dv * VSTR + cc * 8) * 2) = vreg[i]; }
;     };
;     ...
;             for (int kb = 0; kb < 2; ++kb)
; #pragma unroll
;                 for (int i = 0; i < 16; ++i) { const float p = __builtin_amdgcn_exp2f(s[kb][i]); s[kb][i] = p; lsum += p; }
;         } else {
;             const bool need = mx > m_used + 8.0f;
;             if (__builtin_amdgcn_ballot_w64(need) != 0ull) {
;                 const float m_new = need ? mx : m_used;
;                 const float alpha = __builtin_amdgcn_exp2f(m_used - m_new);
;                 lsum *= alpha;
; #pragma unroll
;                 for (int d = 0; d < 4; ++d) O[d] = O[d] * alpha;
;                 m_used = m_new;
;             }
; #pragma unroll
;             for (int kb = 0; kb < 2; ++kb)
; #pragma unroll
;                 for (int i = 0; i < 16; ++i) { const float p = __builtin_amdgcn_exp2f(s[kb][i] - m_used); s[kb][i] = p; lsum += p; }
;         }
; #pragma unroll
;         for (int kb = 0; kb < 2; ++kb)
; #pragma unroll
;             for (int st = 0; st < 2; ++st) {
;                 u32x4 pw;
; #pragma unroll
;                 for (int q = 0; q < 4; ++q) pw[q] = cvt_pk_bf16(s[kb][8 * st + 2 * q], s[kb][8 * st + 2 * q + 1]);
;                 const bf16x8 pf = __builtin_bit_cast(bf16x8, pw);
;                 const LAS unsigned char* vp = vbuf + (r * VSTR + (2 * kb + st) * 16 + 8 * hh) * 2;
; #pragma unroll
;                 for (int d = 0; d < 4; ++d) { const bf16x8 vf = *(const LAS bf16x8*)(vp + d * 32 * VSTR * 2); O[d] = MFMA32(vf, pf, O[d]); }
;             }
;         if (more) store_tile((kt + 1) & 1);
;         __syncthreads();
.LBB0_615:
	v_add_u32_e32 v192, s9, v175
	v_exp_f32_e32 v143, v80
	v_exp_f32_e32 v146, v81
	v_exp_f32_e32 v147, v82
	v_exp_f32_e32 v150, v83
	ds_read_b128 v[80:83], v192 offset:17408
	ds_read_b128 v[176:179], v192 offset:17440
	v_exp_f32_e32 v151, v84
	v_exp_f32_e32 v193, v85
	v_exp_f32_e32 v194, v86
	v_exp_f32_e32 v195, v87
	v_cvt_pk_bf16_f32 v84, v143, v146
	v_cvt_pk_bf16_f32 v85, v147, v150
	v_cvt_pk_bf16_f32 v86, v151, v193
	v_cvt_pk_bf16_f32 v87, v194, v195
	v_add_f32_e32 v143, v173, v143
	v_add_f32_e32 v143, v146, v143
	s_waitcnt lgkmcnt(1)
	v_mfma_f32_32x32x16_bf16 v[48:63], v[80:83], v[84:87], v[48:63]
	ds_read_b128 v[80:83], v192 offset:22016
	ds_read_b128 v[180:183], v192 offset:22048
	v_add_f32_e32 v143, v147, v143
	v_add_f32_e32 v143, v150, v143
	v_exp_f32_e32 v88, v88
	v_exp_f32_e32 v89, v89
	v_add_f32_e32 v143, v151, v143
	v_add_f32_e32 v143, v193, v143
	s_waitcnt lgkmcnt(1)
	v_mfma_f32_32x32x16_bf16 v[32:47], v[80:83], v[84:87], v[32:47]
	ds_read_b128 v[80:83], v192 offset:26624
	ds_read_b128 v[184:187], v192 offset:31232
	ds_read_b128 v[188:191], v192 offset:26656
	v_exp_f32_e32 v90, v90
	v_add_f32_e32 v143, v194, v143
	v_exp_f32_e32 v91, v91
	v_add_f32_e32 v143, v195, v143
	v_exp_f32_e32 v92, v92
	v_exp_f32_e32 v93, v93
	s_waitcnt lgkmcnt(2)
	v_mfma_f32_32x32x16_bf16 v[16:31], v[80:83], v[84:87], v[16:31]
	v_exp_f32_e32 v94, v94
	v_exp_f32_e32 v95, v95
	ds_read_b128 v[80:83], v192 offset:31264
	v_exp_f32_e32 v146, v67
	v_exp_f32_e32 v147, v68
	v_exp_f32_e32 v150, v69
	v_exp_f32_e32 v151, v70
	s_waitcnt lgkmcnt(2)
	v_mfma_f32_32x32x16_bf16 v[0:15], v[184:187], v[84:87], v[0:15]
	v_cvt_pk_bf16_f32 v84, v88, v89
	v_add_f32_e32 v88, v88, v143
	v_add_f32_e32 v88, v89, v88
	v_add_f32_e32 v88, v90, v88
	v_add_f32_e32 v88, v91, v88
	v_add_f32_e32 v88, v92, v88
	v_cvt_pk_bf16_f32 v85, v90, v91
	v_cvt_pk_bf16_f32 v86, v92, v93
	v_cvt_pk_bf16_f32 v87, v94, v95
	v_add_f32_e32 v88, v93, v88
	v_exp_f32_e32 v92, v64
	v_exp_f32_e32 v93, v65
	v_exp_f32_e32 v143, v66
	ds_read_b128 v[64:67], v192 offset:17472
	v_mfma_f32_32x32x16_bf16 v[48:63], v[176:179], v[84:87], v[48:63]
	v_exp_f32_e32 v173, v71
	v_cvt_pk_bf16_f32 v68, v92, v93
	v_cvt_pk_bf16_f32 v69, v143, v146
	v_cvt_pk_bf16_f32 v70, v147, v150
	v_cvt_pk_bf16_f32 v71, v151, v173
	v_exp_f32_e32 v176, v73
	v_exp_f32_e32 v177, v74
	v_mfma_f32_32x32x16_bf16 v[32:47], v[180:183], v[84:87], v[32:47]
	v_exp_f32_e32 v178, v75
	v_exp_f32_e32 v179, v76
	v_exp_f32_e32 v180, v77
	v_exp_f32_e32 v181, v78
	v_exp_f32_e32 v182, v79
	s_cmp_eq_u32 s8, 1
	s_cselect_b32 s8, 0x8c00, 0
	s_waitcnt lgkmcnt(2)
	v_mfma_f32_32x32x16_bf16 v[16:31], v[188:191], v[84:87], v[16:31]
	s_add_i32 s8, s8, 0
	s_add_i32 s42, s42, 8
	s_add_i32 s43, s43, 1
	v_add_u32_e32 v142, 0x100, v142
	v_lshl_add_u64 v[138:139], v[138:139], 0, s[34:35]
	v_lshl_add_u64 v[148:149], v[148:149], 0, s[34:35]
	v_lshl_add_u64 v[144:145], v[144:145], 0, s[36:37]
	s_waitcnt lgkmcnt(1)
	v_mfma_f32_32x32x16_bf16 v[0:15], v[80:83], v[84:87], v[0:15]
	ds_read_b128 v[80:83], v192 offset:22080
	ds_read_b128 v[84:87], v192 offset:17504
	s_cmp_eq_u32 s43, 32
	v_lshl_add_u64 v[140:141], v[140:141], 0, s[36:37]
	s_waitcnt lgkmcnt(2)
	v_mfma_f32_32x32x16_bf16 v[48:63], v[64:67], v[68:71], v[48:63]
	v_add_f32_e32 v64, v94, v88
	v_add_f32_e32 v94, v95, v64
	v_exp_f32_e32 v95, v72
	ds_read_b128 v[64:67], v192 offset:26688
	ds_read_b128 v[88:91], v192 offset:22112
	ds_read_b128 v[72:75], v192 offset:31296
	ds_read_b128 v[76:79], v192 offset:26720
	v_add_f32_e32 v92, v92, v94
	v_add_f32_e32 v92, v93, v92
	s_waitcnt lgkmcnt(5)
	v_mfma_f32_32x32x16_bf16 v[32:47], v[80:83], v[68:71], v[32:47]
	ds_read_b128 v[80:83], v192 offset:31328
	s_waitcnt lgkmcnt(4)
	v_mfma_f32_32x32x16_bf16 v[16:31], v[64:67], v[68:71], v[16:31]
	v_cvt_pk_bf16_f32 v64, v95, v176
	v_cvt_pk_bf16_f32 v65, v177, v178
	v_cvt_pk_bf16_f32 v66, v179, v180
	v_cvt_pk_bf16_f32 v67, v181, v182
	s_waitcnt lgkmcnt(2)
	v_mfma_f32_32x32x16_bf16 v[0:15], v[72:75], v[68:71], v[0:15]
	v_add_f32_e32 v68, v143, v92
	v_add_f32_e32 v68, v146, v68
	v_add_f32_e32 v68, v147, v68
	v_add_f32_e32 v68, v150, v68
	v_add_f32_e32 v68, v151, v68
	v_add_f32_e32 v68, v173, v68
	v_add_f32_e32 v68, v95, v68
	v_mfma_f32_32x32x16_bf16 v[48:63], v[84:87], v[64:67], v[48:63]
	v_add_f32_e32 v68, v176, v68
	v_add_f32_e32 v68, v177, v68
	v_add_f32_e32 v68, v178, v68
	v_add_f32_e32 v68, v179, v68
	v_add_f32_e32 v68, v180, v68
	v_add_f32_e32 v68, v181, v68
	v_add_f32_e32 v173, v182, v68
	v_mfma_f32_32x32x16_bf16 v[32:47], v[88:91], v[64:67], v[32:47]
	v_add3_u32 v68, s8, v167, v166
	v_add3_u32 v69, s8, v169, v168
	v_add_u32_e32 v70, s8, v164
	v_add_u32_e32 v71, s8, v165
	s_waitcnt vmcnt(7)
	ds_write_b128 v68, v[112:115]
	s_waitcnt vmcnt(6)
	ds_write_b128 v69, v[116:119]
	s_waitcnt vmcnt(5)
	ds_write_b128 v70, v[120:123] offset:17408
	s_waitcnt vmcnt(4)
	ds_write_b128 v71, v[124:127] offset:17408
	s_waitcnt lgkmcnt(0)
	s_barrier
	v_mfma_f32_32x32x16_bf16 v[16:31], v[76:79], v[64:67], v[16:31]
	v_mfma_f32_32x32x16_bf16 v[0:15], v[80:83], v[64:67], v[0:15]
	s_cbranch_scc1 .LBB0_622
; #define LAS __attribute__((address_space(3)))
; template <bool DIFF> ...
;     ...
;     auto load_tile = [&](int kt) {
; #pragma unroll
;         for (int i = 0; i < NKC; ++i) { const int c = tid + i * NTHREADS, row = c / CPR, cc = c % CPR; kreg[i] = *(const u32x4*)(Kb + (size_t)(kt * 64 + row) * KLD + cc * 8); }
; #pragma unroll
;         for (int i = 0; i < 2; ++i) { const int c = tid + i * NTHREADS, dv = c >> 3, cc = c & 7; vreg[i] = *(const u32x4*)(Vb + (size_t)dv * SEQ + kt * 64 + cc * 8); }
;     };
;     ...
;         if (more) load_tile(kt + 1);
;         LAS unsigned char* kbuf = lds + (kt & 1) * BUF; LAS unsigned char* vbuf = kbuf + K_BYTES;
;         f32x16 s[2];
;         if (DIFF) {
;             const int tmn = ((const LAS int*)(lds + TMM_OFF))[2 * kt], tmx = ((const LAS int*)(lds + TMM_OFF))[2 * kt + 1];
;             const bool far_hi = __builtin_amdgcn_readfirstlane(tmn - qmax4) >= 512, far_lo = __builtin_amdgcn_readfirstlane(tmx - qmin4) <= -512;
;             if (far_hi || far_lo) {
;                 const float cb = (far_hi ? bias_hi : bias_lo) + nm;
; #pragma unroll
;                 for (int kb = 0; kb < 2; ++kb)
; #pragma unroll
;                     for (int i = 0; i < 16; ++i) s[kb][i] = cb;
;             } else {
; #pragma unroll
;                 for (int kb = 0; kb < 2; ++kb) {
;                     const LAS int* P4 = (const LAS int*)(lds + POS_OFF) + kt * 64 + 32 * kb + 4 * hh;
; #pragma unroll
;                     for (int g = 0; g < 4; ++g) { const i32x4 pk = *(const LAS i32x4*)(P4 + 8 * g);
; #pragma unroll
;                         for (int j = 0; j < 4; ++j) { int d = pk[j] - pq4; d = d < -512 ? -512 : (d > 512 ? 512 : d); s[kb][4 * g + j] = *(const LAS float*)(lds + LUT_OFF + 512 + d) + nm; } }
;                 }
.LBB0_616:
	v_lshl_add_u64 v[64:65], s[12:13], 0, v[140:141]
	v_lshl_add_u64 v[66:67], s[12:13], 0, v[144:145]
	global_load_dwordx4 v[112:115], v[64:65], off
	global_load_dwordx4 v[116:119], v[66:67], off
	v_lshl_add_u64 v[64:65], s[12:13], 0, v[148:149]
	v_lshl_add_u64 v[66:67], s[12:13], 0, v[138:139]
	global_load_dwordx4 v[120:123], v[64:65], off
	global_load_dwordx4 v[124:127], v[66:67], off
	s_cmp_lt_u32 s43, 31
	s_cselect_b32 s98, 0x80, 0
	s_cselect_b32 s100, 0x20000, 0
	s_add_u32 s98, s98, s12
	s_addc_u32 s99, s13, 0
	s_add_u32 s100, s100, s12
	s_addc_u32 s101, s13, 0
	v_lshl_add_u64 v[224:225], s[100:101], 0, v[140:141]
	global_load_dword v223, v[224:225], off
	v_lshl_add_u64 v[224:225], s[100:101], 0, v[144:145]
	global_load_dword v223, v[224:225], off
	v_lshl_add_u64 v[224:225], s[98:99], 0, v[148:149]
	global_load_dword v223, v[224:225], off
	v_lshl_add_u64 v[224:225], s[98:99], 0, v[138:139]
	global_load_dword v223, v[224:225], off
	s_add_i32 s8, s42, 0
	s_add_i32 s8, s8, 0x13d08
	v_mov_b32_e32 v64, s8
	ds_read_b64 v[64:65], v64
	s_waitcnt lgkmcnt(0)
	v_sub_u32_e32 v64, v64, v172
	s_nop 0
	v_readfirstlane_b32 s8, v64
	v_sub_u32_e32 v64, v65, v171
	s_cmpk_gt_i32 s8, 0x1ff
	v_readfirstlane_b32 s40, v64
	s_cselect_b64 s[8:9], -1, 0
	s_cmpk_lt_i32 s40, 0xfe01
	s_cselect_b64 s[40:41], -1, 0
	s_or_b64 s[48:49], s[8:9], s[40:41]
	s_mov_b64 s[40:41], -1
	s_and_b64 vcc, exec, s[48:49]
	s_cbranch_vccnz .LBB0_618
	v_add_u32_e32 v72, 0, v142
	v_add_u32_e32 v64, 0x11900, v72
	ds_read_b128 v[64:67], v64
	v_add_u32_e32 v68, 0x11920, v72
	ds_read_b128 v[68:71], v68
	s_mov_b64 s[40:41], 0
	s_waitcnt lgkmcnt(1)
	v_sub_u32_e32 v64, v64, v162
	v_med3_i32 v64, v64, s75, v158
	v_add_u32_e32 v73, s84, v64
	v_sub_u32_e32 v64, v66, v162
	v_med3_i32 v64, v64, s75, v158
	v_add_u32_e32 v75, s84, v64
	v_sub_u32_e32 v64, v67, v162
	v_med3_i32 v64, v64, s75, v158
	v_add_u32_e32 v76, s84, v64
	s_waitcnt lgkmcnt(0)
	v_sub_u32_e32 v64, v68, v162
	v_med3_i32 v64, v64, s75, v158
	v_add_u32_e32 v68, s84, v64
	v_sub_u32_e32 v64, v69, v162
	v_med3_i32 v64, v64, s75, v158
	v_add_u32_e32 v69, s84, v64
	v_sub_u32_e32 v64, v70, v162
	v_med3_i32 v64, v64, s75, v158
	v_add_u32_e32 v70, s84, v64
	v_sub_u32_e32 v64, v71, v162
	v_sub_u32_e32 v65, v65, v162
	v_med3_i32 v64, v64, s75, v158
	v_med3_i32 v65, v65, s75, v158
	v_add_u32_e32 v71, s84, v64
	v_add_u32_e32 v64, 0x11940, v72
	v_add_u32_e32 v74, s84, v65
	ds_read_b128 v[64:67], v64
	ds_read_b32 v80, v73
	ds_read_b32 v81, v74
	ds_read_b32 v82, v75
	ds_read_b32 v83, v76
	ds_read_b32 v84, v68
	ds_read_b32 v85, v69
	ds_read_b32 v86, v70
	ds_read_b32 v87, v71
	s_waitcnt lgkmcnt(8)
	v_sub_u32_e32 v64, v64, v162
	v_med3_i32 v64, v64, s75, v158
	v_add_u32_e32 v68, 0x11960, v72
	v_add_u32_e32 v73, s84, v64
	v_sub_u32_e32 v64, v65, v162
	ds_read_b128 v[68:71], v68
	v_med3_i32 v64, v64, s75, v158
	v_add_u32_e32 v74, s84, v64
	v_sub_u32_e32 v64, v66, v162
	v_med3_i32 v64, v64, s75, v158
	v_add_u32_e32 v75, s84, v64
	v_sub_u32_e32 v64, v67, v162
	v_med3_i32 v64, v64, s75, v158
	v_add_u32_e32 v76, s84, v64
	s_waitcnt lgkmcnt(0)
	v_sub_u32_e32 v64, v68, v162
	v_med3_i32 v64, v64, s75, v158
	v_add_u32_e32 v68, s84, v64
	v_sub_u32_e32 v64, v69, v162
	v_med3_i32 v64, v64, s75, v158
	v_add_u32_e32 v69, s84, v64
	v_sub_u32_e32 v64, v70, v162
	v_med3_i32 v64, v64, s75, v158
	v_add_u32_e32 v70, s84, v64
	v_sub_u32_e32 v64, v71, v162
	v_med3_i32 v64, v64, s75, v158
	v_add_u32_e32 v71, s84, v64
	v_add_u32_e32 v64, 0x11980, v72
	ds_read_b128 v[64:67], v64
	ds_read_b32 v88, v73
	ds_read_b32 v89, v74
	ds_read_b32 v90, v75
	ds_read_b32 v91, v76
	ds_read_b32 v92, v68
	ds_read_b32 v93, v69
	ds_read_b32 v94, v70
	ds_read_b32 v95, v71
	s_waitcnt lgkmcnt(8)
	v_sub_u32_e32 v64, v64, v162
	v_med3_i32 v64, v64, s75, v158
	v_add_u32_e32 v68, 0x119a0, v72
	v_add_u32_e32 v73, s84, v64
	v_sub_u32_e32 v64, v65, v162
	ds_read_b128 v[68:71], v68
	v_med3_i32 v64, v64, s75, v158
	v_add_u32_e32 v74, s84, v64
	v_sub_u32_e32 v64, v66, v162
	v_med3_i32 v64, v64, s75, v158
	v_add_u32_e32 v75, s84, v64
	v_sub_u32_e32 v64, v67, v162
	v_med3_i32 v64, v64, s75, v158
	v_add_u32_e32 v76, s84, v64
	s_waitcnt lgkmcnt(0)
	v_sub_u32_e32 v64, v68, v162
	v_med3_i32 v64, v64, s75, v158
	v_add_u32_e32 v77, s84, v64
	v_sub_u32_e32 v64, v69, v162
	v_med3_i32 v64, v64, s75, v158
	v_add_u32_e32 v78, s84, v64
	v_sub_u32_e32 v64, v70, v162
	v_sub_u32_e32 v68, v71, v162
	v_med3_i32 v64, v64, s75, v158
	v_med3_i32 v68, v68, s75, v158
	v_add_u32_e32 v79, s84, v64
	v_add_u32_e32 v64, 0x119c0, v72
	v_add_u32_e32 v143, s84, v68
	v_add_u32_e32 v68, 0x119e0, v72
	ds_read_b128 v[64:67], v64
	ds_read_b128 v[68:71], v68
	v_pk_add_f32 v[94:95], v[136:137], v[94:95] op_sel_hi:[0,1]
	v_pk_add_f32 v[92:93], v[136:137], v[92:93] op_sel_hi:[0,1]
	v_pk_add_f32 v[90:91], v[136:137], v[90:91] op_sel_hi:[0,1]
	s_waitcnt lgkmcnt(1)
	v_sub_u32_e32 v64, v64, v162
	v_sub_u32_e32 v65, v65, v162
	v_sub_u32_e32 v66, v66, v162
	v_sub_u32_e32 v67, v67, v162
	s_waitcnt lgkmcnt(0)
	v_sub_u32_e32 v68, v68, v162
	v_sub_u32_e32 v69, v69, v162
	v_sub_u32_e32 v70, v70, v162
	v_sub_u32_e32 v71, v71, v162
	v_med3_i32 v64, v64, s75, v158
	v_med3_i32 v65, v65, s75, v158
	v_med3_i32 v66, v66, s75, v158
	v_med3_i32 v67, v67, s75, v158
	v_med3_i32 v68, v68, s75, v158
	v_med3_i32 v69, v69, s75, v158
	v_med3_i32 v70, v70, s75, v158
	v_med3_i32 v71, v71, s75, v158
	v_add_u32_e32 v64, s84, v64
	v_add_u32_e32 v65, s84, v65
	v_add_u32_e32 v66, s84, v66
	v_add_u32_e32 v67, s84, v67
	v_add_u32_e32 v68, s84, v68
	v_add_u32_e32 v69, s84, v69
	v_add_u32_e32 v70, s84, v70
	v_add_u32_e32 v71, s84, v71
	ds_read_b32 v64, v64
	ds_read_b32 v65, v65
	ds_read_b32 v66, v66
	ds_read_b32 v67, v67
	ds_read_b32 v68, v68
	ds_read_b32 v69, v69
	ds_read_b32 v70, v70
	ds_read_b32 v71, v71
	ds_read_b32 v146, v73
	ds_read_b32 v147, v74
	ds_read_b32 v150, v75
	ds_read_b32 v151, v76
	ds_read_b32 v176, v77
	ds_read_b32 v177, v78
	ds_read_b32 v178, v79
	ds_read_b32 v179, v143
	s_waitcnt lgkmcnt(8)
	v_pk_add_f32 v[78:79], v[136:137], v[70:71] op_sel_hi:[0,1]
	v_pk_add_f32 v[76:77], v[136:137], v[68:69] op_sel_hi:[0,1]
	v_pk_add_f32 v[74:75], v[136:137], v[66:67] op_sel_hi:[0,1]
	v_pk_add_f32 v[72:73], v[136:137], v[64:65] op_sel_hi:[0,1]
	s_waitcnt lgkmcnt(0)
	v_pk_add_f32 v[70:71], v[136:137], v[178:179] op_sel_hi:[0,1]
	v_pk_add_f32 v[68:69], v[136:137], v[176:177] op_sel_hi:[0,1]
	v_pk_add_f32 v[66:67], v[136:137], v[150:151] op_sel_hi:[0,1]
	v_pk_add_f32 v[64:65], v[136:137], v[146:147] op_sel_hi:[0,1]
	v_pk_add_f32 v[88:89], v[136:137], v[88:89] op_sel_hi:[0,1]
	v_pk_add_f32 v[86:87], v[136:137], v[86:87] op_sel_hi:[0,1]
	v_pk_add_f32 v[84:85], v[136:137], v[84:85] op_sel_hi:[0,1]
	v_pk_add_f32 v[82:83], v[136:137], v[82:83] op_sel_hi:[0,1]
	v_pk_add_f32 v[80:81], v[136:137], v[80:81] op_sel_hi:[0,1]

; __global__ void __launch_bounds__(NTHREADS, 2) fwd_megakernel(Args a) {
	.amdhsa_kernel _Z14fwd_megakernel4Args
		.amdhsa_group_segment_fixed_size 0
		.amdhsa_private_segment_fixed_size 0
		.amdhsa_kernarg_size 504
		.amdhsa_user_sgpr_count 2
		.amdhsa_user_sgpr_dispatch_ptr 0
		.amdhsa_user_sgpr_queue_ptr 0
		.amdhsa_user_sgpr_kernarg_segment_ptr 1
		.amdhsa_user_sgpr_dispatch_id 0
		.amdhsa_user_sgpr_kernarg_preload_length 0
		.amdhsa_user_sgpr_kernarg_preload_offset 0
		.amdhsa_user_sgpr_private_segment_size 0
		.amdhsa_uses_dynamic_stack 0
		.amdhsa_enable_private_segment 0
		.amdhsa_system_sgpr_workgroup_id_x 1
		.amdhsa_system_sgpr_workgroup_id_y 0
		.amdhsa_system_sgpr_workgroup_id_z 0
		.amdhsa_system_sgpr_workgroup_info 0
		.amdhsa_system_vgpr_workitem_id 2
		.amdhsa_next_free_vgpr 253
		.amdhsa_next_free_sgpr 102
		.amdhsa_accum_offset 256
		.amdhsa_reserve_vcc 1
		.amdhsa_float_round_mode_32 0
		.amdhsa_float_round_mode_16_64 0
		.amdhsa_float_denorm_mode_32 3
		.amdhsa_float_denorm_mode_16_64 3
		.amdhsa_dx10_clamp 1
		.amdhsa_ieee_mode 1
		.amdhsa_fp16_overflow 0
		.amdhsa_tg_split 0
		.amdhsa_exception_fp_ieee_invalid_op 0
		.amdhsa_exception_fp_denorm_src 0
		.amdhsa_exception_fp_ieee_div_zero 0
		.amdhsa_exception_fp_ieee_overflow 0
		.amdhsa_exception_fp_ieee_underflow 0
		.amdhsa_exception_fp_ieee_inexact 0
		.amdhsa_exception_int_div_zero 0
	.end_amdhsa_kernel

; __global__ void __launch_bounds__(NTHREADS, 2) fwd_megakernel(Args a) {
.Lfunc_end0:
	.size	_Z14fwd_megakernel4Args, .Lfunc_end0-_Z14fwd_megakernel4Args
	.set _Z14fwd_megakernel4Args.num_vgpr, 253
	.set _Z14fwd_megakernel4Args.num_agpr, 0
	.set _Z14fwd_megakernel4Args.numbered_sgpr, 102
	.set _Z14fwd_megakernel4Args.num_named_barrier, 0
	.set _Z14fwd_megakernel4Args.private_seg_size, 0
	.set _Z14fwd_megakernel4Args.uses_vcc, 1
	.set _Z14fwd_megakernel4Args.uses_flat_scratch, 0
	.set _Z14fwd_megakernel4Args.has_dyn_sized_stack, 0
	.set _Z14fwd_megakernel4Args.has_recursion, 0
	.set _Z14fwd_megakernel4Args.has_indirect_call, 0

; __global__ void __launch_bounds__(NTHREADS, 2) fwd_megakernel(Args a) {
amdhsa.kernels:
  - .agpr_count:     0
    .args:
      - .offset:         0
        .size:           248
        .value_kind:     by_value
      - .offset:         248
        .size:           4
        .value_kind:     hidden_block_count_x
      - .offset:         252
        .size:           4
        .value_kind:     hidden_block_count_y
      - .offset:         256
        .size:           4
        .value_kind:     hidden_block_count_z
      - .offset:         260
        .size:           2
        .value_kind:     hidden_group_size_x
      - .offset:         262
        .size:           2
        .value_kind:     hidden_group_size_y
      - .offset:         264
        .size:           2
        .value_kind:     hidden_group_size_z
      - .offset:         266
        .size:           2
        .value_kind:     hidden_remainder_x
      - .offset:         268
        .size:           2
        .value_kind:     hidden_remainder_y
      - .offset:         270
        .size:           2
        .value_kind:     hidden_remainder_z
      - .offset:         288
        .size:           8
        .value_kind:     hidden_global_offset_x
      - .offset:         296
        .size:           8
        .value_kind:     hidden_global_offset_y
      - .offset:         304
        .size:           8
        .value_kind:     hidden_global_offset_z
      - .offset:         312
        .size:           2
        .value_kind:     hidden_grid_dims
      - .offset:         336
        .size:           8
        .value_kind:     hidden_multigrid_sync_arg
      - .offset:         368
        .size:           4
        .value_kind:     hidden_dynamic_lds_size
    .group_segment_fixed_size: 0
    .kernarg_segment_align: 8
    .kernarg_segment_size: 504
    .language:       OpenCL C
    .language_version:
      - 2
      - 0
    .max_flat_workgroup_size: 512
    .name:           _Z14fwd_megakernel4Args
    .private_segment_fixed_size: 0
    .sgpr_count:     108
    .sgpr_spill_count: 0
    .symbol:         _Z14fwd_megakernel4Args.kd
    .uniform_work_group_size: 1
    .uses_dynamic_stack: false
    .vgpr_count:     253
    .vgpr_spill_count: 0
    .wavefront_size: 64
